# retention score loop: first two K reads of each score tile prefetched during the previous tile's MFMA-to-VALU wait, 4-deep read ring
# baseline (speedup 1.0000x reference)
; __device__ __forceinline__ unsigned cvt_pk_bf16(float lo, float hi) { const bf16x2_cv v = __builtin_convertvector((f32x2_cv){lo, hi}, bf16x2_cv); return __builtin_bit_cast(unsigned, v); }
; #define LAS __attribute__((address_space(3)))
; __device__ __forceinline__ void retention_fused(const Params& p, LAS unsigned char* lds, int unit) {
;     ...
; #pragma unroll
;         for (int mt = 0; mt < 2; ++mt)
; #pragma unroll
;             for (int nt = 0; nt < 4; ++nt) { u32x2 w; w.x = cvt_pk_bf16(S[mt][nt][0], S[mt][nt][1]); w.y = cvt_pk_bf16(S[mt][nt][2], S[mt][nt][3]);
;                 *(LAS u32x2*)(St + (nt * 16 + fr) * ST_STRIDE + (32 * wid + 16 * mt + fq * 4) * 2) = w; }
; #pragma unroll
;         for (int i = 0; i < 8; ++i) { const int id = tid + i * NTHREADS, row = id >> 5, cc = id & 31; *(LAS u32x4*)(Ks + row * KS_STRIDE + cc * 16) = *(const u32x4*)(Kg + (size_t)(c * 128 + row) * D + cc * 8); }
; #pragma unroll
;         for (int i = 0; i < 2; ++i) { const int id = tid + i * NTHREADS, row = id >> 3, cc = id & 7;
;             const u32x4 v = *(const u32x4*)(Vg + (size_t)(c * 128 + row) * VD + cc * 8);
;             *(LAS u32x4*)(Vs + row * VS_STRIDE + cc * 16) = v;
;             const float sw = __builtin_amdgcn_exp2f((float)(127 - row) * log2g);
;             u32x4 w; w.x = cvt_pk_bf16(bflo(v.x) * sw, bfhi(v.x) * sw); w.y = cvt_pk_bf16(bflo(v.y) * sw, bfhi(v.y) * sw); w.z = cvt_pk_bf16(bflo(v.z) * sw, bfhi(v.z) * sw); w.w = cvt_pk_bf16(bflo(v.w) * sw, bfhi(v.w) * sw);
;             *(LAS u32x4*)(Vw + row * VS_STRIDE + cc * 16) = w; }
;         bf16x8 qf[8];
; #pragma unroll
;         for (int ks = 0; ks < 8; ++ks) qf[ks] = *(const bf16x8*)(Qg + (size_t)(c * 128 + 16 * wid + fr) * D + ks * 32 + fq * 8);
;         __syncthreads();
.LBB0_1046:
	s_lshl_b32 s23, s57, 17
	v_or_b32_e32 v50, s23, v191
	v_or_b32_e32 v52, s23, v192
	v_or_b32_e32 v58, s23, v193
	v_or_b32_e32 v60, s23, v194
	v_lshlrev_b32_e32 v50, 1, v50
	v_mov_b32_e32 v51, v119
	v_lshlrev_b32_e32 v52, 1, v52
	v_mov_b32_e32 v53, v119
	v_lshlrev_b32_e32 v58, 1, v58
	v_mov_b32_e32 v59, v119
	v_lshlrev_b32_e32 v60, 1, v60
	v_mov_b32_e32 v61, v119
	v_lshl_add_u64 v[50:51], v[120:121], 0, v[50:51]
	v_lshl_add_u64 v[54:55], v[120:121], 0, v[52:53]
	v_lshl_add_u64 v[58:59], v[120:121], 0, v[58:59]
	v_lshl_add_u64 v[62:63], v[120:121], 0, v[60:61]
	global_load_dwordx4 v[50:53], v[50:51], off
	s_nop 0
	global_load_dwordx4 v[54:57], v[54:55], off
	s_nop 0
	global_load_dwordx4 v[58:61], v[58:59], off
	s_nop 0
	global_load_dwordx4 v[62:65], v[62:63], off
	v_or_b32_e32 v66, s23, v195
	v_or_b32_e32 v68, s23, v196
	v_lshlrev_b32_e32 v66, 1, v66
	v_mov_b32_e32 v67, v119
	v_lshlrev_b32_e32 v68, 1, v68
	v_mov_b32_e32 v69, v119
	v_or_b32_e32 v74, s23, v197
	v_lshl_add_u64 v[66:67], v[120:121], 0, v[66:67]
	v_lshl_add_u64 v[70:71], v[120:121], 0, v[68:69]
	v_lshlrev_b32_e32 v74, 1, v74
	v_mov_b32_e32 v75, v119
	v_add_lshl_u32 v76, s23, v198, 1
	v_mov_b32_e32 v77, v119
	global_load_dwordx4 v[66:69], v[66:67], off
	s_nop 0
	global_load_dwordx4 v[70:73], v[70:71], off
	v_lshl_add_u64 v[74:75], v[120:121], 0, v[74:75]
	v_lshl_add_u64 v[78:79], v[120:121], 0, v[76:77]
	global_load_dwordx4 v[74:77], v[74:75], off
	s_nop 0
	global_load_dwordx4 v[78:81], v[78:79], off
	s_lshl_b32 s23, s57, 18
	v_or_b32_e32 v82, s23, v199
	v_lshlrev_b32_e32 v82, 1, v82
	v_mov_b32_e32 v83, v119
	v_lshl_add_u64 v[82:83], v[122:123], 0, v[82:83]
	global_load_dwordx4 v[178:181], v[82:83], off
	v_add_lshl_u32 v82, s23, v201, 1
	v_mov_b32_e32 v83, v119
	v_lshl_add_u64 v[82:83], v[122:123], 0, v[82:83]
	global_load_dwordx4 v[222:225], v[82:83], off
	s_lshl_b32 s23, s57, 7
	v_mov_b32_e32 v83, v119
	v_add_u32_e32 v82, s23, v186
	v_lshlrev_b64 v[82:83], 11, v[82:83]
	v_lshl_add_u64 v[110:111], v[124:125], 0, v[82:83]
	global_load_dwordx4 v[82:85], v[110:111], off
	global_load_dwordx4 v[86:89], v[110:111], off offset:64
	global_load_dwordx4 v[90:93], v[110:111], off offset:128
	global_load_dwordx4 v[94:97], v[110:111], off offset:192
	global_load_dwordx4 v[98:101], v[110:111], off offset:256
	v_cvt_pk_bf16_f32 v102, v30, v31
	v_cvt_pk_bf16_f32 v103, v32, v33
	v_cvt_pk_bf16_f32 v112, v2, v3
	v_cvt_pk_bf16_f32 v113, v4, v5
	v_cvt_pk_bf16_f32 v104, v18, v19
	v_cvt_pk_bf16_f32 v105, v20, v21
	v_cvt_pk_bf16_f32 v106, v22, v23
	v_cvt_pk_bf16_f32 v107, v24, v25
	v_cvt_pk_bf16_f32 v226, v6, v7
	v_cvt_pk_bf16_f32 v227, v8, v9
	v_add_u32_e32 v117, 0x2000, v208
	v_cvt_pk_bf16_f32 v228, v10, v11
	v_cvt_pk_bf16_f32 v229, v12, v13
	v_add_u32_e32 v161, 0x4000, v208
	ds_write2_b64 v208, v[102:103], v[112:113] offset1:4
	ds_write2_b64 v117, v[104:105], v[226:227] offset0:32 offset1:36
	ds_write2_b64 v161, v[106:107], v[228:229] offset0:64 offset1:68
	global_load_dwordx4 v[102:105], v[110:111], off offset:320
	v_cvt_pk_bf16_f32 v108, v26, v27
	v_cvt_pk_bf16_f32 v109, v28, v29
	v_cvt_pk_bf16_f32 v230, v14, v15
	v_cvt_pk_bf16_f32 v231, v16, v17
	v_add_u32_e32 v163, 0x6000, v208
	v_lshl_or_b32 v161, s58, 5, v183
	v_lshlrev_b32_e32 v182, 9, v161
	s_mov_b32 s26, 0
	v_mov_b32_e32 v117, v204
	s_mov_b32 s27, s37
	ds_write2_b64 v163, v[108:109], v[230:231] offset0:96 offset1:100
	s_waitcnt vmcnt(15)
	ds_write_b128 v209, v[50:53]
	s_waitcnt vmcnt(14)
	ds_write_b128 v210, v[54:57]
	s_waitcnt vmcnt(13)
	ds_write_b128 v209, v[58:61] offset:16896
	s_waitcnt vmcnt(12)
	ds_write_b128 v211, v[62:65]
	global_load_dwordx4 v[106:109], v[110:111], off offset:384
	s_waitcnt vmcnt(12)
	ds_write_b128 v209, v[66:69] offset:33792
	s_waitcnt vmcnt(11)
	ds_write_b128 v212, v[70:73]
	s_waitcnt vmcnt(10)
	ds_write_b128 v209, v[74:77] offset:50688
	global_load_dwordx4 v[110:113], v[110:111], off offset:448
	v_add_u32_e32 v50, v184, v200
	s_waitcnt vmcnt(10)
	ds_write_b128 v213, v[78:81]
	v_mov_b32_e32 v163, v139
	s_waitcnt vmcnt(9)
	ds_write_b128 v50, v[178:181]
	v_lshlrev_b32_e32 v50, 16, v178
	v_and_b32_e32 v51, 0xffff0000, v178
	v_lshlrev_b32_e32 v52, 16, v179
	v_and_b32_e32 v53, 0xffff0000, v179
	v_pk_mul_f32 v[50:51], v[140:141], v[50:51]
	v_pk_mul_f32 v[52:53], v[140:141], v[52:53]
	v_cvt_pk_bf16_f32 v50, v50, v51
	v_cvt_pk_bf16_f32 v51, v52, v53
	v_lshlrev_b32_e32 v52, 16, v180
	v_and_b32_e32 v53, 0xffff0000, v180
	v_lshlrev_b32_e32 v54, 16, v181
	v_and_b32_e32 v55, 0xffff0000, v181
	v_pk_mul_f32 v[52:53], v[140:141], v[52:53]
	v_pk_mul_f32 v[54:55], v[140:141], v[54:55]
	v_cvt_pk_bf16_f32 v52, v52, v53
	v_cvt_pk_bf16_f32 v53, v54, v55
	v_add_u32_e32 v54, v185, v200
	ds_write_b128 v54, v[50:53]
	v_add_u32_e32 v50, v184, v202
	s_waitcnt vmcnt(8)
	ds_write_b128 v50, v[222:225]
	v_lshlrev_b32_e32 v50, 16, v222
	v_and_b32_e32 v51, 0xffff0000, v222
	v_lshlrev_b32_e32 v52, 16, v223
	v_and_b32_e32 v53, 0xffff0000, v223
	v_pk_mul_f32 v[50:51], v[142:143], v[50:51]
	v_pk_mul_f32 v[52:53], v[142:143], v[52:53]
	v_cvt_pk_bf16_f32 v50, v50, v51
	v_cvt_pk_bf16_f32 v51, v52, v53
	v_lshlrev_b32_e32 v52, 16, v224
	v_and_b32_e32 v53, 0xffff0000, v224
	v_lshlrev_b32_e32 v54, 16, v225
	v_and_b32_e32 v55, 0xffff0000, v225
	v_pk_mul_f32 v[52:53], v[142:143], v[52:53]
	v_pk_mul_f32 v[54:55], v[142:143], v[54:55]
	v_cvt_pk_bf16_f32 v52, v52, v53
	v_cvt_pk_bf16_f32 v53, v54, v55
	v_add_u32_e32 v54, v185, v202
	ds_write_b128 v54, v[50:53]
	s_waitcnt lgkmcnt(0)
	s_barrier
; #define LAS __attribute__((address_space(3)))
; #define SAMPLE_ISSUE(hb) do { _Pragma("unroll") for (int i = 0; i < 4; ++i) s0v[i] = __builtin_nontemporal_load((const f32x4*)(S0 + (size_t)(dbase + 4 * ((hb) * 4 + i)) * 512)); } while (0)
; __device__ __forceinline__ void retention_fused(const Params& p, LAS unsigned char* lds, int unit) {
;     ...
;         SAMPLE_ISSUE(0);
;         f32x4 o[4];
; #pragma unroll
;         for (int nt = 0; nt < 4; ++nt) {
;             o[nt] = (f32x4){0.f, 0.f, 0.f, 0.f};
; #pragma unroll
;             for (int ks = 0; ks < 8; ++ks) { const bf16x8 sf = *(const LAS bf16x8*)(St + (nt * 16 + fr) * ST_STRIDE + ks * 64 + fq * 16);
;                 o[nt] = __builtin_amdgcn_mfma_f32_16x16x32_bf16(qf[ks], sf, o[nt], 0, 0, 0); }
; #pragma unroll
;             for (int r = 0; r < 4; ++r) o[nt][r] *= __builtin_amdgcn_exp2f((float)(16 * wid + fq * 4 + r + 1) * log2g);
;         }
	ds_read_b128 v[50:53], v214
	ds_read_b128 v[54:57], v214 offset:64
	s_waitcnt vmcnt(7) lgkmcnt(1)
	v_mfma_f32_16x16x32_bf16 v[50:53], v[82:85], v[50:53], 0
	v_lshlrev_b32_e32 v178, 11, v161
	v_mov_b32_e32 v179, v119
	v_lshl_add_u64 v[180:181], v[164:165], 0, v[178:179]
	s_waitcnt vmcnt(6) lgkmcnt(0)
	v_mfma_f32_16x16x32_bf16 v[50:53], v[86:89], v[54:57], v[50:53]
	ds_read_b128 v[54:57], v214 offset:128
	ds_read_b128 v[58:61], v214 offset:192
	v_add_co_u32_e32 v70, vcc, s52, v180
	s_waitcnt vmcnt(5) lgkmcnt(1)
	v_mfma_f32_16x16x32_bf16 v[50:53], v[90:93], v[54:57], v[50:53]
	v_addc_co_u32_e32 v71, vcc, 0, v181, vcc
	s_waitcnt vmcnt(4) lgkmcnt(0)
	v_mfma_f32_16x16x32_bf16 v[50:53], v[94:97], v[58:61], v[50:53]
	ds_read_b128 v[54:57], v214 offset:256
	ds_read_b128 v[58:61], v214 offset:320
	s_waitcnt vmcnt(3) lgkmcnt(1)
	v_mfma_f32_16x16x32_bf16 v[50:53], v[98:101], v[54:57], v[50:53]
	s_waitcnt vmcnt(2) lgkmcnt(0)
	v_mfma_f32_16x16x32_bf16 v[50:53], v[102:105], v[58:61], v[50:53]
	ds_read_b128 v[54:57], v214 offset:384
	ds_read_b128 v[58:61], v214 offset:448
	s_waitcnt vmcnt(1) lgkmcnt(1)
	v_mfma_f32_16x16x32_bf16 v[50:53], v[106:109], v[54:57], v[50:53]
	s_waitcnt vmcnt(0) lgkmcnt(0)
	v_mfma_f32_16x16x32_bf16 v[50:53], v[110:113], v[58:61], v[50:53]
	ds_read_b128 v[54:57], v214 offset:8448
	ds_read_b128 v[58:61], v214 offset:8512
	s_waitcnt lgkmcnt(1)
	v_mfma_f32_16x16x32_bf16 v[54:57], v[82:85], v[54:57], 0
	s_waitcnt lgkmcnt(0)
	v_mfma_f32_16x16x32_bf16 v[54:57], v[86:89], v[58:61], v[54:57]
	ds_read_b128 v[58:61], v214 offset:8576
	ds_read_b128 v[62:65], v214 offset:8640
	s_waitcnt lgkmcnt(1)
	v_mfma_f32_16x16x32_bf16 v[54:57], v[90:93], v[58:61], v[54:57]
	s_waitcnt lgkmcnt(0)
	v_mfma_f32_16x16x32_bf16 v[54:57], v[94:97], v[62:65], v[54:57]
	ds_read_b128 v[58:61], v214 offset:8704
	ds_read_b128 v[62:65], v214 offset:8768
	s_waitcnt lgkmcnt(1)
	v_mfma_f32_16x16x32_bf16 v[54:57], v[98:101], v[58:61], v[54:57]
	s_waitcnt lgkmcnt(0)
	v_mfma_f32_16x16x32_bf16 v[54:57], v[102:105], v[62:65], v[54:57]
	ds_read_b128 v[58:61], v214 offset:8832
	ds_read_b128 v[62:65], v214 offset:8896
	s_waitcnt lgkmcnt(1)
	v_mfma_f32_16x16x32_bf16 v[54:57], v[106:109], v[58:61], v[54:57]
	s_waitcnt lgkmcnt(0)
	v_mfma_f32_16x16x32_bf16 v[54:57], v[110:113], v[62:65], v[54:57]
	ds_read_b128 v[58:61], v214 offset:16896
	ds_read_b128 v[62:65], v214 offset:16960
	s_waitcnt lgkmcnt(1)
	v_mfma_f32_16x16x32_bf16 v[58:61], v[82:85], v[58:61], 0
	s_waitcnt lgkmcnt(0)
	v_mfma_f32_16x16x32_bf16 v[58:61], v[86:89], v[62:65], v[58:61]
	ds_read_b128 v[62:65], v214 offset:17024
	ds_read_b128 v[66:69], v214 offset:17088
	s_waitcnt lgkmcnt(1)
	v_mfma_f32_16x16x32_bf16 v[58:61], v[90:93], v[62:65], v[58:61]
	s_waitcnt lgkmcnt(0)
	v_mfma_f32_16x16x32_bf16 v[58:61], v[94:97], v[66:69], v[58:61]
	ds_read_b128 v[62:65], v214 offset:17152
	ds_read_b128 v[66:69], v214 offset:17216
	s_waitcnt lgkmcnt(1)
	v_mfma_f32_16x16x32_bf16 v[58:61], v[98:101], v[62:65], v[58:61]
	ds_read_b128 v[62:65], v214 offset:17280
	s_waitcnt lgkmcnt(1)
	v_mfma_f32_16x16x32_bf16 v[58:61], v[102:105], v[66:69], v[58:61]
	ds_read_b128 v[66:69], v214 offset:17344
	s_waitcnt lgkmcnt(1)
	v_mfma_f32_16x16x32_bf16 v[58:61], v[106:109], v[62:65], v[58:61]
	ds_read_b128 v[62:65], v214 offset:25344
	global_load_dwordx4 v[78:81], v[180:181], off nt
	global_load_dwordx4 v[74:77], v[70:71], off nt
	ds_read_b128 v[226:229], v214 offset:25536
	s_waitcnt lgkmcnt(2)
	v_mfma_f32_16x16x32_bf16 v[222:225], v[110:113], v[66:69], v[58:61]
	v_add_co_u32_e32 v66, vcc, s51, v180
	s_nop 1
	ds_read_b128 v[58:61], v214 offset:25408
	s_waitcnt lgkmcnt(2)
	v_mfma_f32_16x16x32_bf16 v[62:65], v[82:85], v[62:65], 0
	v_addc_co_u32_e32 v67, vcc, 0, v181, vcc
	v_add_co_u32_e32 v68, vcc, s53, v180
	s_waitcnt lgkmcnt(0)
	v_mfma_f32_16x16x32_bf16 v[58:61], v[86:89], v[58:61], v[62:65]
	v_addc_co_u32_e32 v69, vcc, 0, v181, vcc
	s_nop 2
	ds_read_b128 v[62:65], v214 offset:25472
	global_load_dwordx4 v[70:73], v[66:67], off nt
	s_nop 0
	global_load_dwordx4 v[66:69], v[68:69], off nt
	s_waitcnt lgkmcnt(0)
	v_mfma_f32_16x16x32_bf16 v[58:61], v[90:93], v[62:65], v[58:61]
	ds_read_b128 v[62:65], v214 offset:25600
	ds_read_b128 v[230:233], v214 offset:25728
	v_mfma_f32_16x16x32_bf16 v[58:61], v[94:97], v[226:229], v[58:61]
	ds_read_b128 v[226:229], v214 offset:25664
	s_waitcnt lgkmcnt(2)
	v_mfma_f32_16x16x32_bf16 v[58:61], v[98:101], v[62:65], v[58:61]
	v_mul_f32_e64 v64, v148, v52
	v_mul_f32_e64 v65, v149, v53
	v_pk_mul_f32 v[62:63], v[144:145], v[50:51]
	ds_read_b128 v[50:53], v214 offset:25792
	s_waitcnt lgkmcnt(1)
	v_mfma_f32_16x16x32_bf16 v[226:229], v[102:105], v[226:229], v[58:61]
	v_mfma_f32_16x16x32_bf16 v[226:229], v[106:109], v[230:233], v[226:229]
	s_nop 1
	v_mul_f32_e64 v60, v148, v56
	v_mul_f32_e64 v61, v149, v57
	v_pk_mul_f32 v[58:59], v[144:145], v[54:55]
	v_pk_mul_f32 v[56:57], v[148:149], v[224:225]
	s_waitcnt lgkmcnt(0)
	v_mfma_f32_16x16x32_bf16 v[50:53], v[110:113], v[50:53], v[226:229]
	v_mul_f32_e64 v54, v144, v222
	v_mul_f32_e64 v55, v145, v223
	s_nop 5
	v_pk_mul_f32 v[52:53], v[148:149], v[52:53]
	v_pk_mul_f32 v[50:51], v[144:145], v[50:51]
	ds_read_b128 v[248:251], v163
	ds_read_b128 v[252:255], v163 offset:64
	s_branch .LBB0_1049
; #define LAS __attribute__((address_space(3)))
; __device__ __forceinline__ void retention_fused(const Params& p, LAS unsigned char* lds, int unit) {
;     ...
;                 for (int t = 0; t < 2; ++t) { const int jt = 2 * a + t;
;                     sc[t] = (f32x4){0.f, 0.f, 0.f, 0.f};
;                     if (jt <= wid) {
; #pragma unroll
;                         for (int ks = 0; ks < 8; ++ks) { const bf16x8 kf = *(const LAS bf16x8*)(Ks + (jt * 16 + fr) * KS_STRIDE + ks * 64 + fq * 16);
;                             sc[t] = __builtin_amdgcn_mfma_f32_16x16x32_bf16(kf, qf[ks], sc[t], 0, 0, 0); }
;                         const float tf = __builtin_amdgcn_exp2f((float)(16 * (wid - jt)) * log2g);
; #pragma unroll
;                         for (int r = 0; r < 4; ++r) { const int dij = 16 * (wid - jt) + fr - fq * 4 - r;
;                             sc[t][r] = dij >= 0 ? sc[t][r] * (tf * __builtin_amdgcn_exp2f((float)(fr - fq * 4 - r) * log2g)) : 0.f; }
;                     } }
.LBB0_1047:
	ds_read_b128 v[230:233], v224 offset:8576
	ds_read_b128 v[234:237], v224 offset:8640
	ds_read_b128 v[238:241], v224 offset:8704
	ds_read_b128 v[242:245], v224 offset:8768
	v_add_u32_e32 v246, -16, v225
	s_add_i32 s28, s27, -16
	s_waitcnt lgkmcnt(5)
	v_mfma_f32_16x16x32_bf16 v[226:229], v[248:251], v[82:85], 0
	s_waitcnt lgkmcnt(4)
	v_mfma_f32_16x16x32_bf16 v[226:229], v[252:255], v[86:89], v[226:229]
	s_waitcnt lgkmcnt(3)
	v_mfma_f32_16x16x32_bf16 v[226:229], v[230:233], v[90:93], v[226:229]
	ds_read_b128 v[230:233], v224 offset:8832
	s_waitcnt lgkmcnt(3)
	v_mfma_f32_16x16x32_bf16 v[226:229], v[234:237], v[94:97], v[226:229]
	ds_read_b128 v[234:237], v224 offset:8896
	s_waitcnt lgkmcnt(3)
	v_mfma_f32_16x16x32_bf16 v[224:227], v[238:241], v[98:101], v[226:229]
	v_sub_u32_e32 v238, v246, v130
	v_sub_u32_e32 v239, v246, v1
	v_cmp_lt_i32_e32 vcc, -1, v238
	s_waitcnt lgkmcnt(2)
	v_mfma_f32_16x16x32_bf16 v[224:227], v[242:245], v[102:105], v[224:227]
	v_cvt_f32_i32_e32 v228, s28
	v_sub_u32_e32 v240, v246, v152
	v_mul_f32_e32 v228, v153, v228
	s_waitcnt lgkmcnt(1)
	v_mfma_f32_16x16x32_bf16 v[224:227], v[230:233], v[106:109], v[224:227]
	v_exp_f32_e32 v228, v228
	v_sub_u32_e32 v232, v246, v115
	v_pk_mul_f32 v[230:231], v[150:151], v[228:229] op_sel_hi:[1,0]
	s_waitcnt lgkmcnt(0)
	v_mfma_f32_16x16x32_bf16 v[224:227], v[234:237], v[110:113], v[224:227]
	ds_read_b128 v[248:251], v163 offset:16896
	ds_read_b128 v[252:255], v163 offset:16960
	v_pk_mul_f32 v[228:229], v[154:155], v[228:229] op_sel_hi:[1,0]
	s_nop 4
	v_pk_mul_f32 v[224:225], v[230:231], v[224:225]
	v_pk_mul_f32 v[228:229], v[228:229], v[226:227]
	v_cndmask_b32_e32 v226, 0, v224, vcc
	v_cmp_lt_i32_e32 vcc, -1, v239
	s_nop 1
	v_cndmask_b32_e32 v224, 0, v225, vcc
	v_cmp_lt_i32_e32 vcc, -1, v240
	s_nop 1
	v_cndmask_b32_e32 v225, 0, v228, vcc
	v_cmp_lt_i32_e32 vcc, -1, v232
	s_nop 1
	v_cndmask_b32_e32 v227, 0, v229, vcc

; #define LAS __attribute__((address_space(3)))
; __device__ __forceinline__ void retention_fused(const Params& p, LAS unsigned char* lds, int unit) {
;     ...
;                 for (int t = 0; t < 2; ++t) { const int jt = 2 * a + t;
;                     sc[t] = (f32x4){0.f, 0.f, 0.f, 0.f};
;                     if (jt <= wid) {
; #pragma unroll
;                         for (int ks = 0; ks < 8; ++ks) { const bf16x8 kf = *(const LAS bf16x8*)(Ks + (jt * 16 + fr) * KS_STRIDE + ks * 64 + fq * 16);
;                             sc[t] = __builtin_amdgcn_mfma_f32_16x16x32_bf16(kf, qf[ks], sc[t], 0, 0, 0); }
;                         const float tf = __builtin_amdgcn_exp2f((float)(16 * (wid - jt)) * log2g);
; #pragma unroll
;                         for (int r = 0; r < 4; ++r) { const int dij = 16 * (wid - jt) + fr - fq * 4 - r;
;                             sc[t][r] = dij >= 0 ? sc[t][r] * (tf * __builtin_amdgcn_exp2f((float)(fr - fq * 4 - r) * log2g)) : 0.f; }
;                     } }
.LBB0_1049:
	v_add_u32_e32 v224, 0, v163
	ds_read_b128 v[230:233], v224 offset:128
	ds_read_b128 v[234:237], v224 offset:192
	ds_read_b128 v[238:241], v224 offset:256
	ds_read_b128 v[242:245], v224 offset:320
	v_cvt_f32_i32_e32 v179, s27
	v_add_u32_e32 v225, s27, v114
	s_waitcnt lgkmcnt(5)
	v_mfma_f32_16x16x32_bf16 v[226:229], v[248:251], v[82:85], 0
	v_sub_u32_e32 v221, v225, v1
	v_mul_f32_e32 v179, v153, v179
	v_exp_f32_e32 v222, v179
	s_waitcnt lgkmcnt(4)
	v_mfma_f32_16x16x32_bf16 v[226:229], v[252:255], v[86:89], v[226:229]
	v_sub_u32_e32 v246, v225, v130
	v_cmp_lt_i32_e32 vcc, -1, v221
	s_waitcnt lgkmcnt(3)
	v_mfma_f32_16x16x32_bf16 v[226:229], v[230:233], v[90:93], v[226:229]
	ds_read_b128 v[230:233], v224 offset:384
	s_cmp_lt_u32 s26, s17
	s_waitcnt lgkmcnt(3)
	v_mfma_f32_16x16x32_bf16 v[226:229], v[234:237], v[94:97], v[226:229]
	ds_read_b128 v[234:237], v224 offset:448
	s_waitcnt lgkmcnt(3)
	v_mfma_f32_16x16x32_bf16 v[226:229], v[238:241], v[98:101], v[226:229]
	s_waitcnt lgkmcnt(2)
	v_mfma_f32_16x16x32_bf16 v[226:229], v[242:245], v[102:105], v[226:229]
	v_sub_u32_e32 v238, v225, v115
	s_waitcnt lgkmcnt(1)
	v_mfma_f32_16x16x32_bf16 v[226:229], v[230:233], v[106:109], v[226:229]
	v_mul_f32_e64 v230, v150, v222
	v_mul_f32_e64 v231, v151, v222
	v_pk_mul_f32 v[222:223], v[154:155], v[222:223] op_sel_hi:[1,0]
	v_sub_u32_e32 v232, v225, v152
	s_waitcnt lgkmcnt(0)
	v_mfma_f32_16x16x32_bf16 v[226:229], v[234:237], v[110:113], v[226:229]
	ds_read_b128 v[248:251], v224 offset:8448
	ds_read_b128 v[252:255], v224 offset:8512
	s_nop 5
	v_pk_mul_f32 v[226:227], v[230:231], v[226:227]
	v_pk_mul_f32 v[228:229], v[222:223], v[228:229]
	v_cndmask_b32_e32 v179, 0, v227, vcc
	v_cmp_lt_i32_e32 vcc, -1, v246
	s_nop 1
	v_cndmask_b32_e32 v221, 0, v226, vcc
	v_cmp_lt_i32_e32 vcc, -1, v238
	v_mov_b32_e32 v226, 0
	s_nop 0
	v_cndmask_b32_e32 v222, 0, v229, vcc
	v_cmp_lt_i32_e32 vcc, -1, v232
	s_nop 1
	v_cndmask_b32_e32 v223, 0, v228, vcc
	s_cbranch_scc1 .LBB0_1047
	v_mov_b32_e32 v224, 0
	v_mov_b32_e32 v225, 0
	v_mov_b32_e32 v227, 0
	s_branch .LBB0_1048
